# retpost: loop-invariant gn rows loaded once before the loop; per-pair reload + vmcnt(0) (which also waited for the previous store ack) removed
# speedup vs baseline: 1.0164x; 1.0033x over previous
; __device__ __forceinline__ void phase_retpost(const Params& p) {
;   int tid = threadIdx.x; asm volatile("" : "+v"(tid));
;   const int w = tid >> 6, lane = tid & 63;
;   unsigned char* ws = p.ws;
;   const bf16_t* RO = (const bf16_t*)(ws + WS_RO); const bf16_t* RG = (const bf16_t*)(ws + WS_RG);
;   bf16_t* ACAT = (bf16_t*)(ws + WS_ACAT);
;   for (int pr0 = (blockIdx.x * 8 + w) * 8; pr0 < TOKP * 8; pr0 += gridDim.x * 8 * 8) {
;     u32x2 xr[8], sr[8];
; #pragma unroll
;     for (int q = 0; q < 8; ++q) {
;       const int pr = pr0 + q, r = pr >> 3, h = pr & 7;
;       const size_t o = (size_t)r * 2048 + h * 256 + 4 * lane;
;       xr[q] = *(const u32x2*)(RO + o);
;       sr[q] = *(const u32x2*)(RG + o);
;     }
;     ...
;       const f32x4 gn = *(const f32x4*)(p.in[12] + h * 256 + 4 * lane);
.LBB0_169:
	s_and_b64 vcc, exec, s[36:37]
	s_cbranch_vccz .LBB0_246
	s_cmp_gt_i32 s26, 1
	s_mov_b64 s[36:37], -1
	s_cbranch_scc0 .LBB0_248
	v_readlane_b32 s64, v253, 3
	s_cmp_gt_i32 s26, 2
	v_readlane_b32 s65, v253, 4
	s_cbranch_scc0 .LBB0_176
	v_mov_b32_e32 v0, v226
	v_readlane_b32 s29, v252, 45
	v_ashrrev_i32_e32 v1, 3, v0
	v_and_b32_e32 v1, -8, v1
	v_add_u32_e32 v62, s29, v1
	s_mov_b32 s29, 0x10000
	v_cmp_gt_i32_e32 vcc, s29, v62
	s_and_saveexec_b64 s[38:39], vcc
	v_readlane_b32 s60, v253, 60
	v_readlane_b32 s61, v253, 61
	v_readlane_b32 s62, v252, 46
	s_mov_b32 s63, 0x109000
	s_mov_b32 s66, 0x800000
	s_mov_b32 s30, 0x3b800000
	s_cbranch_execz .LBB0_175
	v_and_b32_e32 v1, 64, v230
	v_add_u32_e32 v1, 64, v1
	v_xor_b32_e32 v2, 32, v230
	v_cmp_lt_i32_e32 vcc, v2, v1
	v_lshlrev_b32_e32 v0, 2, v0
	v_and_b32_e32 v0, 0xfc, v0
	v_cndmask_b32_e32 v2, v230, v2, vcc
	v_lshlrev_b32_e32 v63, 2, v2
	v_xor_b32_e32 v2, 16, v230
	v_cmp_lt_i32_e32 vcc, v2, v1
	v_readlane_b32 s34, v252, 47
	v_lshlrev_b32_e32 v64, 2, v0
	v_cndmask_b32_e32 v2, v230, v2, vcc
	v_lshlrev_b32_e32 v66, 2, v2
	v_xor_b32_e32 v2, 8, v230
	v_cmp_lt_i32_e32 vcc, v2, v1
	v_readlane_b32 s35, v252, 48
	v_readlane_b32 s44, v251, 0
	v_cndmask_b32_e32 v2, v230, v2, vcc
	v_lshlrev_b32_e32 v67, 2, v2
	v_xor_b32_e32 v2, 4, v230
	v_cmp_lt_i32_e32 vcc, v2, v1
	v_lshl_add_u64 v[6:7], s[34:35], 0, v[64:65]
	v_readlane_b32 s34, v252, 49
	v_cndmask_b32_e32 v2, v230, v2, vcc
	v_lshlrev_b32_e32 v68, 2, v2
	v_xor_b32_e32 v2, 2, v230
	v_cmp_lt_i32_e32 vcc, v2, v1
	v_readlane_b32 s35, v252, 50
	v_readlane_b32 s52, v251, 8
	v_cndmask_b32_e32 v2, v230, v2, vcc
	v_lshl_add_u64 v[8:9], s[34:35], 0, v[64:65]
	v_readlane_b32 s34, v252, 51
	v_lshlrev_b32_e32 v69, 2, v2
	v_xor_b32_e32 v2, 1, v230
	v_readlane_b32 s35, v252, 52
	v_cmp_lt_i32_e32 vcc, v2, v1
	v_readlane_b32 s53, v251, 9
	v_lshl_add_u64 v[10:11], s[34:35], 0, v[64:65]
	v_readlane_b32 s34, v252, 53
	v_cndmask_b32_e32 v1, v230, v2, vcc
	v_readlane_b32 s35, v252, 54
	v_lshlrev_b32_e32 v70, 2, v1
	v_lshl_add_u64 v[4:5], s[52:53], 0, v[64:65]
	v_lshl_add_u64 v[12:13], s[34:35], 0, v[64:65]
	s_mov_b64 s[42:43], 0
	v_lshlrev_b32_e32 v64, 1, v0
	v_readlane_b32 s45, v251, 1
	v_readlane_b32 s46, v251, 2
	v_readlane_b32 s47, v251, 3
	v_readlane_b32 s48, v251, 4
	v_readlane_b32 s49, v251, 5
	v_readlane_b32 s50, v251, 6
	v_readlane_b32 s51, v251, 7
	v_readlane_b32 s54, v251, 10
	v_readlane_b32 s55, v251, 11
	v_readlane_b32 s56, v251, 12
	v_readlane_b32 s57, v251, 13
	v_readlane_b32 s58, v251, 14
	v_readlane_b32 s59, v251, 15
	global_load_dwordx4 v[80:83], v[4:5], off
	global_load_dwordx4 v[84:87], v[4:5], off offset:1024
	global_load_dwordx4 v[88:91], v[4:5], off offset:2048
	global_load_dwordx4 v[92:95], v[4:5], off offset:3072
	global_load_dwordx4 v[96:99], v[6:7], off
	global_load_dwordx4 v[100:103], v[8:9], off
	global_load_dwordx4 v[104:107], v[10:11], off
	global_load_dwordx4 v[108:111], v[12:13], off
.LBB0_174:
	v_ashrrev_i32_e32 v0, 3, v62
	v_ashrrev_i32_e32 v1, 31, v0
	v_lshlrev_b64 v[2:3], 12, v[0:1]
	v_or_b32_e32 v2, v2, v64
	v_lshl_add_u64 v[14:15], s[94:95], 0, v[2:3]
	global_load_dwordx2 v[46:47], v[14:15], off
	v_lshl_add_u64 v[14:15], s[60:61], 0, v[2:3]
	global_load_dwordx2 v[24:25], v[14:15], off
	v_or_b32_e32 v14, 0x200, v2
	v_mov_b32_e32 v15, v3
	v_lshl_add_u64 v[16:17], s[94:95], 0, v[14:15]
	global_load_dwordx2 v[48:49], v[16:17], off
	v_lshlrev_b64 v[0:1], 13, v[0:1]
	v_lshl_add_u64 v[0:1], s[24:25], 0, v[0:1]
	v_lshl_add_u64 v[44:45], v[0:1], 0, v[64:65]
	v_lshl_add_u64 v[14:15], s[60:61], 0, v[14:15]
	global_load_dwordx2 v[42:43], v[14:15], off
	v_or_b32_e32 v14, 0x400, v2
	v_mov_b32_e32 v15, v3
	v_lshl_add_u64 v[16:17], s[94:95], 0, v[14:15]
	v_lshl_add_u64 v[14:15], s[60:61], 0, v[14:15]
	global_load_dwordx2 v[40:41], v[16:17], off
	global_load_dwordx2 v[36:37], v[14:15], off
	v_or_b32_e32 v14, 0x600, v2
	v_mov_b32_e32 v15, v3
	v_lshl_add_u64 v[16:17], s[94:95], 0, v[14:15]
	v_lshl_add_u64 v[14:15], s[60:61], 0, v[14:15]
	global_load_dwordx2 v[38:39], v[16:17], off
	global_load_dwordx2 v[34:35], v[14:15], off
	v_or_b32_e32 v14, 0x800, v2
	v_mov_b32_e32 v15, v3
	v_lshl_add_u64 v[16:17], s[94:95], 0, v[14:15]
	v_lshl_add_u64 v[14:15], s[60:61], 0, v[14:15]
	global_load_dwordx2 v[32:33], v[16:17], off
	global_load_dwordx2 v[28:29], v[14:15], off
	v_or_b32_e32 v14, 0xa00, v2
	v_mov_b32_e32 v15, v3
	v_lshl_add_u64 v[16:17], s[94:95], 0, v[14:15]
	v_lshl_add_u64 v[14:15], s[60:61], 0, v[14:15]
	global_load_dwordx2 v[30:31], v[16:17], off
	global_load_dwordx2 v[26:27], v[14:15], off
	v_or_b32_e32 v14, 0xc00, v2
	v_mov_b32_e32 v15, v3
	v_lshl_add_u64 v[16:17], s[94:95], 0, v[14:15]
	v_lshl_add_u64 v[14:15], s[60:61], 0, v[14:15]
	v_or_b32_e32 v2, 0xe00, v2
	global_load_dwordx2 v[20:21], v[14:15], off
	v_lshl_add_u64 v[14:15], s[94:95], 0, v[2:3]
	v_lshl_add_u64 v[2:3], s[60:61], 0, v[2:3]
	global_load_dwordx2 v[22:23], v[16:17], off
	global_load_dwordx2 v[18:19], v[14:15], off
	s_mov_b32 s36, 0x3727c5ac
	global_load_dwordx2 v[14:15], v[2:3], off
	s_mov_b64 s[34:35], 0x109800
	v_lshl_add_u64 v[16:17], v[44:45], 0, s[34:35]
	v_add_u32_e32 v62, s62, v62
	s_mov_b32 s29, 0xffff
	s_waitcnt vmcnt(0)
	v_lshlrev_b32_e32 v50, 16, v46
	v_and_b32_e32 v51, 0xffff0000, v46
	v_lshlrev_b32_e32 v52, 16, v47
	v_add_f32_e32 v0, v50, v51
	v_and_b32_e32 v53, 0xffff0000, v47
	v_add_f32_e32 v0, v0, v52
	v_add_f32_e32 v0, v0, v53
	v_mov_b32_e32 v1, v0
	s_nop 1
	v_permlane32_swap_b32_e32 v1, v0
	s_waitcnt vmcnt(13)
	v_lshlrev_b32_e32 v46, 16, v48
	v_and_b32_e32 v47, 0xffff0000, v48
	v_lshlrev_b32_e32 v54, 16, v24
	v_and_b32_e32 v55, 0xffff0000, v24
	s_waitcnt lgkmcnt(0)
; __device__ __forceinline__ u32x2 pack4(f32x4 v) { u32x2 r; r[0] = cvt_pk(v[0], v[1]); r[1] = cvt_pk(v[2], v[3]); return r; }
; __device__ __forceinline__ f32x4 unpack4(u32x2 u) { f32x4 r; r[0] = bflo(u[0]); r[1] = bfhi(u[0]); r[2] = bflo(u[1]); r[3] = bfhi(u[1]); return r; }
; __device__ __forceinline__ float wave_sum(float v) {
; #pragma unroll
;   for (int o = 32; o >= 1; o >>= 1) v += __shfl_xor(v, o);
;   return v;
; }
; __device__ __forceinline__ void phase_retpost(const Params& p) {
;     ...
; #pragma unroll
;     for (int q = 0; q < 8; ++q) {
;       const int pr = pr0 + q, r = pr >> 3, h = pr & 7;
;       const f32x4 x = unpack4(xr[q]);
;       const float mean = wave_sum(x[0] + x[1] + x[2] + x[3]) * (1.0f / 256.0f);
;       const f32x4 d = x - mean;
;       const float var = wave_sum(d[0] * d[0] + d[1] * d[1] + d[2] * d[2] + d[3] * d[3]) * (1.0f / 256.0f);
;       const float rstd = rsqrtf(var + LN_EPS);
;       const f32x4 gn = *(const f32x4*)(p.in[12] + h * 256 + 4 * lane);
;       const f32x4 sg = unpack4(sr[q]);
;       *(u32x2*)(ACAT + (size_t)r * 4096 + 1024 + h * 256 + 4 * lane) = pack4(d * rstd * gn * sg);
;     }
	v_add_f32_e32 v0, v0, v1
	v_mov_b32_e32 v1, v0
	s_nop 1
	v_permlane16_swap_b32_e32 v1, v0
	v_lshlrev_b32_e32 v48, 16, v49
	v_add_f32_e32 v24, v46, v47
	v_and_b32_e32 v49, 0xffff0000, v49
	v_add_f32_e32 v24, v24, v48
	s_waitcnt lgkmcnt(0)
	v_add_f32_e32 v0, v0, v1
	s_nop 1
	v_mov_b32_dpp v1, v0 row_ror:8 row_mask:0xf bank_mask:0xf
	v_add_f32_e32 v24, v24, v49
	v_lshlrev_b32_e32 v56, 16, v25
	v_and_b32_e32 v57, 0xffff0000, v25
	v_mov_b32_e32 v25, v24
	s_nop 1
	v_permlane32_swap_b32_e32 v25, v24
	s_waitcnt lgkmcnt(0)
	v_add_f32_e32 v0, v0, v1
	s_nop 1
	v_mov_b32_dpp v1, v0 row_ror:4 row_mask:0xf bank_mask:0xf
	s_waitcnt lgkmcnt(0)
	v_add_f32_e32 v24, v24, v25
	v_mov_b32_e32 v25, v24
	s_nop 1
	v_permlane16_swap_b32_e32 v25, v24
	s_waitcnt lgkmcnt(0)
	v_add_f32_e32 v0, v0, v1
	s_nop 1
	v_mov_b32_dpp v1, v0 quad_perm:[2,3,0,1] row_mask:0xf bank_mask:0xf
	s_waitcnt lgkmcnt(0)
	v_add_f32_e32 v24, v24, v25
	s_nop 1
	v_mov_b32_dpp v25, v24 row_ror:8 row_mask:0xf bank_mask:0xf
	s_waitcnt lgkmcnt(0)
	v_add_f32_e32 v0, v0, v1
	s_nop 1
	v_mov_b32_dpp v1, v0 quad_perm:[1,0,3,2] row_mask:0xf bank_mask:0xf
	s_waitcnt lgkmcnt(0)
	v_add_f32_e32 v24, v24, v25
	s_nop 1
	v_mov_b32_dpp v25, v24 row_ror:4 row_mask:0xf bank_mask:0xf
	s_waitcnt lgkmcnt(0)
	v_add_f32_e32 v0, v0, v1
	v_fmac_f32_e32 v51, 0xbb800000, v0
	v_fmac_f32_e32 v50, 0xbb800000, v0
	v_fmac_f32_e32 v53, 0xbb800000, v0
	v_fmac_f32_e32 v52, 0xbb800000, v0
	v_mov_b64_e32 v[0:1], v[80:81]
	v_mov_b64_e32 v[2:3], v[82:83]
	s_waitcnt lgkmcnt(0)
	v_add_f32_e32 v24, v24, v25
	s_nop 1
	v_mov_b32_dpp v25, v24 quad_perm:[2,3,0,1] row_mask:0xf bank_mask:0xf
	v_pk_mul_f32 v[60:61], v[50:51], v[50:51]
	v_pk_mul_f32 v[58:59], v[52:53], v[52:53]
	v_mov_b32_e32 v75, v60
	s_waitcnt lgkmcnt(0)
	v_add_f32_e32 v24, v24, v25
	s_nop 1
	v_mov_b32_dpp v25, v24 quad_perm:[1,0,3,2] row_mask:0xf bank_mask:0xf
	s_waitcnt lgkmcnt(0)
	v_add_f32_e32 v24, v24, v25
	v_fmac_f32_e32 v47, 0xbb800000, v24
	v_fmac_f32_e32 v46, 0xbb800000, v24
	v_fmac_f32_e32 v49, 0xbb800000, v24
	v_fmac_f32_e32 v48, 0xbb800000, v24
	v_pk_mul_f32 v[72:73], v[46:47], v[46:47]
	v_pk_mul_f32 v[24:25], v[48:49], v[48:49]
	v_mov_b32_e32 v74, v72
	v_mov_b32_e32 v60, v73
	v_pk_add_f32 v[60:61], v[74:75], v[60:61]
	v_mov_b32_e32 v72, v24
	v_mov_b32_e32 v73, v58
	v_pk_add_f32 v[60:61], v[72:73], v[60:61]
	v_mov_b32_e32 v58, v25
	v_pk_add_f32 v[24:25], v[58:59], v[60:61]
	v_mov_b32_e32 v59, v25
	s_nop 1
	v_permlane32_swap_b32_e32 v59, v25
	v_mov_b32_e32 v58, v24
	s_nop 1
	v_permlane32_swap_b32_e32 v58, v24
	s_waitcnt lgkmcnt(0)
	v_pk_add_f32 v[24:25], v[24:25], v[58:59]
	v_mov_b32_e32 v59, v25
	s_nop 1
	v_permlane16_swap_b32_e32 v59, v25
	v_mov_b32_e32 v58, v24
	s_nop 1
	v_permlane16_swap_b32_e32 v58, v24
	s_waitcnt lgkmcnt(0)
	v_pk_add_f32 v[24:25], v[24:25], v[58:59]
	s_nop 1
	v_mov_b32_dpp v59, v25 row_ror:8 row_mask:0xf bank_mask:0xf
	s_nop 1
	v_mov_b32_dpp v58, v24 row_ror:8 row_mask:0xf bank_mask:0xf
	s_waitcnt lgkmcnt(0)
	v_pk_add_f32 v[24:25], v[24:25], v[58:59]
	s_nop 1
	v_mov_b32_dpp v59, v25 row_ror:4 row_mask:0xf bank_mask:0xf
	s_nop 1
	v_mov_b32_dpp v58, v24 row_ror:4 row_mask:0xf bank_mask:0xf
	s_waitcnt lgkmcnt(0)
	v_pk_add_f32 v[24:25], v[24:25], v[58:59]
	s_nop 1
	v_mov_b32_dpp v59, v25 quad_perm:[2,3,0,1] row_mask:0xf bank_mask:0xf
	s_nop 1
	v_mov_b32_dpp v58, v24 quad_perm:[2,3,0,1] row_mask:0xf bank_mask:0xf
	s_waitcnt lgkmcnt(0)
	v_pk_add_f32 v[24:25], v[24:25], v[58:59]
	s_nop 1
	v_mov_b32_dpp v59, v25 quad_perm:[1,0,3,2] row_mask:0xf bank_mask:0xf
	s_nop 1
	v_mov_b32_dpp v58, v24 quad_perm:[1,0,3,2] row_mask:0xf bank_mask:0xf
	s_waitcnt lgkmcnt(0)
	v_pk_add_f32 v[58:59], v[24:25], v[58:59]
	v_mov_b64_e32 v[24:25], s[36:37]
	v_pk_fma_f32 v[58:59], v[58:59], s[30:31], v[24:25] op_sel_hi:[1,0,0]
	s_nop 0
	v_mul_f32_e32 v60, 0x4b800000, v59
	v_cmp_gt_f32_e64 s[36:37], s66, v59
	v_cmp_gt_f32_e32 vcc, s66, v58
	s_nop 0
	v_cndmask_b32_e64 v59, v59, v60, s[36:37]
	v_rsq_f32_e32 v59, v59
	s_nop 0
	v_mul_f32_e32 v60, 0x45800000, v59
	v_cndmask_b32_e64 v60, v59, v60, s[36:37]
	v_pk_mul_f32 v[52:53], v[52:53], v[60:61] op_sel_hi:[1,0]
	v_pk_mul_f32 v[50:51], v[50:51], v[60:61] op_sel_hi:[1,0]
	v_pk_mul_f32 v[2:3], v[2:3], v[52:53]
	v_pk_mul_f32 v[0:1], v[0:1], v[50:51]
	v_pk_mul_f32 v[2:3], v[2:3], v[56:57]
	v_pk_mul_f32 v[0:1], v[0:1], v[54:55]
	v_lshlrev_b32_e32 v50, 16, v42
	v_cvt_pk_bf16_f32 v0, v0, v1
	v_cvt_pk_bf16_f32 v1, v2, v3
	v_add_co_u32_e64 v2, s[36:37], s63, v44
	v_and_b32_e32 v51, 0xffff0000, v42
	s_nop 0
	v_addc_co_u32_e64 v3, s[36:37], 0, v45, s[36:37]
	global_store_dwordx2 v[2:3], v[0:1], off offset:2048
	v_mul_f32_e32 v0, 0x4b800000, v58
	v_cndmask_b32_e32 v0, v58, v0, vcc
	v_rsq_f32_e32 v0, v0
	v_lshlrev_b32_e32 v42, 16, v43
	v_and_b32_e32 v43, 0xffff0000, v43
	v_mul_f32_e32 v1, 0x45800000, v0
	v_cndmask_b32_e32 v44, v0, v1, vcc
	v_mov_b64_e32 v[0:1], v[84:85]
	v_mov_b64_e32 v[2:3], v[86:87]
	v_pk_mul_f32 v[48:49], v[48:49], v[44:45] op_sel_hi:[1,0]
	v_pk_mul_f32 v[44:45], v[46:47], v[44:45] op_sel_hi:[1,0]
	v_pk_mul_f32 v[2:3], v[2:3], v[48:49]
	v_pk_mul_f32 v[0:1], v[0:1], v[44:45]
	v_pk_mul_f32 v[2:3], v[2:3], v[42:43]
	v_pk_mul_f32 v[0:1], v[0:1], v[50:51]
	v_lshlrev_b32_e32 v42, 16, v40
	v_cvt_pk_bf16_f32 v0, v0, v1
	v_cvt_pk_bf16_f32 v1, v2, v3
	v_and_b32_e32 v43, 0xffff0000, v40
	global_store_dwordx2 v[16:17], v[0:1], off offset:512
	v_lshlrev_b32_e32 v40, 16, v41
	v_add_f32_e32 v0, v42, v43
	v_and_b32_e32 v41, 0xffff0000, v41
	v_add_f32_e32 v0, v0, v40
	v_add_f32_e32 v0, v0, v41
	v_mov_b32_e32 v1, v0
	s_nop 1
	v_permlane32_swap_b32_e32 v1, v0
	v_lshlrev_b32_e32 v48, 16, v36
	v_and_b32_e32 v49, 0xffff0000, v36
	v_lshlrev_b32_e32 v50, 16, v37
	v_and_b32_e32 v51, 0xffff0000, v37
	s_waitcnt lgkmcnt(0)
; __device__ __forceinline__ u32x2 pack4(f32x4 v) { u32x2 r; r[0] = cvt_pk(v[0], v[1]); r[1] = cvt_pk(v[2], v[3]); return r; }
; __device__ __forceinline__ f32x4 unpack4(u32x2 u) { f32x4 r; r[0] = bflo(u[0]); r[1] = bfhi(u[0]); r[2] = bflo(u[1]); r[3] = bfhi(u[1]); return r; }
; __device__ __forceinline__ float wave_sum(float v) {
; #pragma unroll
;   for (int o = 32; o >= 1; o >>= 1) v += __shfl_xor(v, o);
;   return v;
; }
; __device__ __forceinline__ void phase_retpost(const Params& p) {
;     ...
; #pragma unroll
;     for (int q = 0; q < 8; ++q) {
;       const int pr = pr0 + q, r = pr >> 3, h = pr & 7;
;       const f32x4 x = unpack4(xr[q]);
;       const float mean = wave_sum(x[0] + x[1] + x[2] + x[3]) * (1.0f / 256.0f);
;       const f32x4 d = x - mean;
;       const float var = wave_sum(d[0] * d[0] + d[1] * d[1] + d[2] * d[2] + d[3] * d[3]) * (1.0f / 256.0f);
;       const float rstd = rsqrtf(var + LN_EPS);
;       const f32x4 gn = *(const f32x4*)(p.in[12] + h * 256 + 4 * lane);
;       const f32x4 sg = unpack4(sr[q]);
;       *(u32x2*)(ACAT + (size_t)r * 4096 + 1024 + h * 256 + 4 * lane) = pack4(d * rstd * gn * sg);
;     }
	v_add_f32_e32 v0, v0, v1
	v_mov_b32_e32 v1, v0
	s_nop 1
	v_permlane16_swap_b32_e32 v1, v0
	v_lshlrev_b32_e32 v36, 16, v38
	v_and_b32_e32 v37, 0xffff0000, v38
	v_lshlrev_b32_e32 v38, 16, v39
	v_add_f32_e32 v52, v36, v37
	s_waitcnt lgkmcnt(0)
	v_add_f32_e32 v0, v0, v1
	s_nop 1
	v_mov_b32_dpp v1, v0 row_ror:8 row_mask:0xf bank_mask:0xf
	v_and_b32_e32 v39, 0xffff0000, v39
	v_add_f32_e32 v52, v52, v38
	v_add_f32_e32 v52, v52, v39
	v_mov_b32_e32 v53, v52
	s_nop 1
	v_permlane32_swap_b32_e32 v53, v52
	s_waitcnt lgkmcnt(0)
	v_add_f32_e32 v0, v0, v1
	s_nop 1
	v_mov_b32_dpp v1, v0 row_ror:4 row_mask:0xf bank_mask:0xf
	s_waitcnt lgkmcnt(0)
	v_add_f32_e32 v52, v52, v53
	v_mov_b32_e32 v53, v52
	s_nop 1
	v_permlane16_swap_b32_e32 v53, v52
	s_waitcnt lgkmcnt(0)
	v_add_f32_e32 v0, v0, v1
	s_nop 1
	v_mov_b32_dpp v1, v0 quad_perm:[2,3,0,1] row_mask:0xf bank_mask:0xf
	s_waitcnt lgkmcnt(0)
	v_add_f32_e32 v52, v52, v53
	s_nop 1
	v_mov_b32_dpp v53, v52 row_ror:8 row_mask:0xf bank_mask:0xf
	s_waitcnt lgkmcnt(0)
	v_add_f32_e32 v0, v0, v1
	s_nop 1
	v_mov_b32_dpp v1, v0 quad_perm:[1,0,3,2] row_mask:0xf bank_mask:0xf
	s_waitcnt lgkmcnt(0)
	v_add_f32_e32 v52, v52, v53
	s_nop 1
	v_mov_b32_dpp v53, v52 row_ror:4 row_mask:0xf bank_mask:0xf
	s_waitcnt lgkmcnt(0)
	v_add_f32_e32 v0, v0, v1
	v_fmac_f32_e32 v43, 0xbb800000, v0
	v_fmac_f32_e32 v42, 0xbb800000, v0
	v_fmac_f32_e32 v41, 0xbb800000, v0
	v_fmac_f32_e32 v40, 0xbb800000, v0
	v_mov_b64_e32 v[0:1], v[88:89]
	v_mov_b64_e32 v[2:3], v[90:91]
	s_waitcnt lgkmcnt(0)
	v_add_f32_e32 v52, v52, v53
	s_nop 1
	v_mov_b32_dpp v53, v52 quad_perm:[2,3,0,1] row_mask:0xf bank_mask:0xf
	v_pk_mul_f32 v[46:47], v[42:43], v[42:43]
	v_pk_mul_f32 v[44:45], v[40:41], v[40:41]
	v_mov_b32_e32 v57, v46
	s_waitcnt lgkmcnt(0)
	v_add_f32_e32 v52, v52, v53
	s_nop 1
	v_mov_b32_dpp v53, v52 quad_perm:[1,0,3,2] row_mask:0xf bank_mask:0xf
	s_waitcnt lgkmcnt(0)
	v_add_f32_e32 v52, v52, v53
	v_fmac_f32_e32 v37, 0xbb800000, v52
	v_fmac_f32_e32 v36, 0xbb800000, v52
	v_fmac_f32_e32 v39, 0xbb800000, v52
	v_fmac_f32_e32 v38, 0xbb800000, v52
	v_pk_mul_f32 v[54:55], v[36:37], v[36:37]
	v_pk_mul_f32 v[52:53], v[38:39], v[38:39]
	v_mov_b32_e32 v56, v54
	v_mov_b32_e32 v46, v55
	v_pk_add_f32 v[46:47], v[56:57], v[46:47]
	v_mov_b32_e32 v54, v52
	v_mov_b32_e32 v55, v44
	v_pk_add_f32 v[46:47], v[54:55], v[46:47]
	v_mov_b32_e32 v44, v53
	v_pk_add_f32 v[44:45], v[44:45], v[46:47]
	v_mov_b32_e32 v47, v45
	s_nop 1
	v_permlane32_swap_b32_e32 v47, v45
	v_mov_b32_e32 v46, v44
	s_nop 1
	v_permlane32_swap_b32_e32 v46, v44
	s_waitcnt lgkmcnt(0)
	v_pk_add_f32 v[44:45], v[44:45], v[46:47]
	v_mov_b32_e32 v47, v45
	s_nop 1
	v_permlane16_swap_b32_e32 v47, v45
	v_mov_b32_e32 v46, v44
	s_nop 1
	v_permlane16_swap_b32_e32 v46, v44
	s_waitcnt lgkmcnt(0)
	v_pk_add_f32 v[44:45], v[44:45], v[46:47]
	s_nop 1
	v_mov_b32_dpp v47, v45 row_ror:8 row_mask:0xf bank_mask:0xf
	s_nop 1
	v_mov_b32_dpp v46, v44 row_ror:8 row_mask:0xf bank_mask:0xf
	s_waitcnt lgkmcnt(0)
	v_pk_add_f32 v[44:45], v[44:45], v[46:47]
	s_nop 1
	v_mov_b32_dpp v47, v45 row_ror:4 row_mask:0xf bank_mask:0xf
	s_nop 1
	v_mov_b32_dpp v46, v44 row_ror:4 row_mask:0xf bank_mask:0xf
	s_waitcnt lgkmcnt(0)
	v_pk_add_f32 v[44:45], v[44:45], v[46:47]
	s_nop 1
	v_mov_b32_dpp v47, v45 quad_perm:[2,3,0,1] row_mask:0xf bank_mask:0xf
	s_nop 1
	v_mov_b32_dpp v46, v44 quad_perm:[2,3,0,1] row_mask:0xf bank_mask:0xf
	s_waitcnt lgkmcnt(0)
	v_pk_add_f32 v[44:45], v[44:45], v[46:47]
	s_nop 1
	v_mov_b32_dpp v47, v45 quad_perm:[1,0,3,2] row_mask:0xf bank_mask:0xf
	s_nop 1
	v_mov_b32_dpp v46, v44 quad_perm:[1,0,3,2] row_mask:0xf bank_mask:0xf
	s_waitcnt lgkmcnt(0)
	v_pk_add_f32 v[44:45], v[44:45], v[46:47]
	s_nop 0
	v_pk_fma_f32 v[44:45], v[44:45], s[30:31], v[24:25] op_sel_hi:[1,0,0]
	s_nop 0
	v_mul_f32_e32 v46, 0x4b800000, v45
	v_cmp_gt_f32_e64 s[36:37], s66, v45
	v_cmp_gt_f32_e32 vcc, s66, v44
	s_nop 0
	v_cndmask_b32_e64 v45, v45, v46, s[36:37]
	v_rsq_f32_e32 v45, v45
	s_nop 0
	v_mul_f32_e32 v46, 0x45800000, v45
	v_cndmask_b32_e64 v46, v45, v46, s[36:37]
	v_pk_mul_f32 v[40:41], v[40:41], v[46:47] op_sel_hi:[1,0]
	v_pk_mul_f32 v[42:43], v[42:43], v[46:47] op_sel_hi:[1,0]
	v_pk_mul_f32 v[2:3], v[2:3], v[40:41]
	v_pk_mul_f32 v[0:1], v[0:1], v[42:43]
	v_pk_mul_f32 v[2:3], v[2:3], v[50:51]
	v_pk_mul_f32 v[0:1], v[0:1], v[48:49]
	v_lshlrev_b32_e32 v42, 16, v34
	v_cvt_pk_bf16_f32 v0, v0, v1
	v_cvt_pk_bf16_f32 v1, v2, v3
	global_store_dwordx2 v[16:17], v[0:1], off offset:1024
	v_mul_f32_e32 v0, 0x4b800000, v44
	v_cndmask_b32_e32 v0, v44, v0, vcc
	v_rsq_f32_e32 v0, v0
	v_and_b32_e32 v43, 0xffff0000, v34
	v_lshlrev_b32_e32 v34, 16, v35
	v_and_b32_e32 v35, 0xffff0000, v35
	v_mul_f32_e32 v1, 0x45800000, v0
	v_cndmask_b32_e32 v40, v0, v1, vcc
	v_mov_b64_e32 v[0:1], v[92:93]
	v_mov_b64_e32 v[2:3], v[94:95]
	v_pk_mul_f32 v[38:39], v[38:39], v[40:41] op_sel_hi:[1,0]
	v_pk_mul_f32 v[36:37], v[36:37], v[40:41] op_sel_hi:[1,0]
	v_lshlrev_b32_e32 v40, 16, v28
	v_and_b32_e32 v41, 0xffff0000, v28
	v_lshlrev_b32_e32 v28, 16, v30
	v_pk_mul_f32 v[0:1], v[0:1], v[36:37]
	v_pk_mul_f32 v[2:3], v[2:3], v[38:39]
	v_pk_mul_f32 v[0:1], v[0:1], v[42:43]
	v_pk_mul_f32 v[2:3], v[2:3], v[34:35]
	v_cvt_pk_bf16_f32 v0, v0, v1
	v_cvt_pk_bf16_f32 v1, v2, v3
	v_lshlrev_b32_e32 v34, 16, v32
	v_and_b32_e32 v35, 0xffff0000, v32
	global_store_dwordx2 v[16:17], v[0:1], off offset:1536
	v_lshlrev_b32_e32 v32, 16, v33
	v_add_f32_e32 v0, v34, v35
	v_and_b32_e32 v33, 0xffff0000, v33
	v_add_f32_e32 v0, v0, v32
	v_add_f32_e32 v0, v0, v33
	v_mov_b32_e32 v1, v0
	s_nop 1
	v_permlane32_swap_b32_e32 v1, v0
	v_lshlrev_b32_e32 v42, 16, v29
	v_and_b32_e32 v43, 0xffff0000, v29
	v_and_b32_e32 v29, 0xffff0000, v30
	v_lshlrev_b32_e32 v30, 16, v31
	s_waitcnt lgkmcnt(0)
; __device__ __forceinline__ u32x2 pack4(f32x4 v) { u32x2 r; r[0] = cvt_pk(v[0], v[1]); r[1] = cvt_pk(v[2], v[3]); return r; }
; __device__ __forceinline__ f32x4 unpack4(u32x2 u) { f32x4 r; r[0] = bflo(u[0]); r[1] = bfhi(u[0]); r[2] = bflo(u[1]); r[3] = bfhi(u[1]); return r; }
; __device__ __forceinline__ float wave_sum(float v) {
; #pragma unroll
;   for (int o = 32; o >= 1; o >>= 1) v += __shfl_xor(v, o);
;   return v;
; }
; __device__ __forceinline__ void phase_retpost(const Params& p) {
;     ...
; #pragma unroll
;     for (int q = 0; q < 8; ++q) {
;       const int pr = pr0 + q, r = pr >> 3, h = pr & 7;
;       const f32x4 x = unpack4(xr[q]);
;       const float mean = wave_sum(x[0] + x[1] + x[2] + x[3]) * (1.0f / 256.0f);
;       const f32x4 d = x - mean;
;       const float var = wave_sum(d[0] * d[0] + d[1] * d[1] + d[2] * d[2] + d[3] * d[3]) * (1.0f / 256.0f);
;       const float rstd = rsqrtf(var + LN_EPS);
;       const f32x4 gn = *(const f32x4*)(p.in[12] + h * 256 + 4 * lane);
;       const f32x4 sg = unpack4(sr[q]);
;       *(u32x2*)(ACAT + (size_t)r * 4096 + 1024 + h * 256 + 4 * lane) = pack4(d * rstd * gn * sg);
;     }
	v_add_f32_e32 v0, v0, v1
	v_mov_b32_e32 v1, v0
	s_nop 1
	v_permlane16_swap_b32_e32 v1, v0
	v_add_f32_e32 v44, v28, v29
	v_and_b32_e32 v31, 0xffff0000, v31
	v_add_f32_e32 v44, v44, v30
	v_add_f32_e32 v44, v44, v31
	s_waitcnt lgkmcnt(0)
	v_add_f32_e32 v0, v0, v1
	s_nop 1
	v_mov_b32_dpp v1, v0 row_ror:8 row_mask:0xf bank_mask:0xf
	v_mov_b32_e32 v45, v44
	s_nop 1
	v_permlane32_swap_b32_e32 v45, v44
	s_waitcnt lgkmcnt(0)
	v_add_f32_e32 v0, v0, v1
	s_nop 1
	v_mov_b32_dpp v1, v0 row_ror:4 row_mask:0xf bank_mask:0xf
	s_waitcnt lgkmcnt(0)
	v_add_f32_e32 v44, v44, v45
	v_mov_b32_e32 v45, v44
	s_nop 1
	v_permlane16_swap_b32_e32 v45, v44
	s_waitcnt lgkmcnt(0)
	v_add_f32_e32 v0, v0, v1
	s_nop 1
	v_mov_b32_dpp v1, v0 quad_perm:[2,3,0,1] row_mask:0xf bank_mask:0xf
	s_waitcnt lgkmcnt(0)
	v_add_f32_e32 v44, v44, v45
	s_nop 1
	v_mov_b32_dpp v45, v44 row_ror:8 row_mask:0xf bank_mask:0xf
	s_waitcnt lgkmcnt(0)
	v_add_f32_e32 v0, v0, v1
	s_nop 1
	v_mov_b32_dpp v1, v0 quad_perm:[1,0,3,2] row_mask:0xf bank_mask:0xf
	s_waitcnt lgkmcnt(0)
	v_add_f32_e32 v44, v44, v45
	s_nop 1
	v_mov_b32_dpp v45, v44 row_ror:4 row_mask:0xf bank_mask:0xf
	s_waitcnt lgkmcnt(0)
	v_add_f32_e32 v0, v0, v1
	v_fmac_f32_e32 v35, 0xbb800000, v0
	v_fmac_f32_e32 v34, 0xbb800000, v0
	v_fmac_f32_e32 v33, 0xbb800000, v0
	v_fmac_f32_e32 v32, 0xbb800000, v0
	v_mov_b64_e32 v[0:1], v[96:97]
	v_mov_b64_e32 v[2:3], v[98:99]
	s_waitcnt lgkmcnt(0)
	v_add_f32_e32 v44, v44, v45
	s_nop 1
	v_mov_b32_dpp v45, v44 quad_perm:[2,3,0,1] row_mask:0xf bank_mask:0xf
	v_pk_mul_f32 v[38:39], v[34:35], v[34:35]
	v_pk_mul_f32 v[36:37], v[32:33], v[32:33]
	v_mov_b32_e32 v49, v38
	s_waitcnt lgkmcnt(0)
	v_add_f32_e32 v44, v44, v45
	s_nop 1
	v_mov_b32_dpp v45, v44 quad_perm:[1,0,3,2] row_mask:0xf bank_mask:0xf
	s_waitcnt lgkmcnt(0)
	v_add_f32_e32 v44, v44, v45
	v_fmac_f32_e32 v29, 0xbb800000, v44
	v_fmac_f32_e32 v28, 0xbb800000, v44
	v_fmac_f32_e32 v31, 0xbb800000, v44
	v_fmac_f32_e32 v30, 0xbb800000, v44
	v_pk_mul_f32 v[46:47], v[28:29], v[28:29]
	v_pk_mul_f32 v[44:45], v[30:31], v[30:31]
	v_mov_b32_e32 v48, v46
	v_mov_b32_e32 v38, v47
	v_pk_add_f32 v[38:39], v[48:49], v[38:39]
	v_mov_b32_e32 v46, v44
	v_mov_b32_e32 v47, v36
	v_pk_add_f32 v[38:39], v[46:47], v[38:39]
	v_mov_b32_e32 v36, v45
	v_pk_add_f32 v[36:37], v[36:37], v[38:39]
	v_mov_b32_e32 v39, v37
	s_nop 1
	v_permlane32_swap_b32_e32 v39, v37
	v_mov_b32_e32 v38, v36
	s_nop 1
	v_permlane32_swap_b32_e32 v38, v36
	s_waitcnt lgkmcnt(0)
	v_pk_add_f32 v[36:37], v[36:37], v[38:39]
	v_mov_b32_e32 v39, v37
	s_nop 1
	v_permlane16_swap_b32_e32 v39, v37
	v_mov_b32_e32 v38, v36
	s_nop 1
	v_permlane16_swap_b32_e32 v38, v36
	s_waitcnt lgkmcnt(0)
	v_pk_add_f32 v[36:37], v[36:37], v[38:39]
	s_nop 1
	v_mov_b32_dpp v39, v37 row_ror:8 row_mask:0xf bank_mask:0xf
	s_nop 1
	v_mov_b32_dpp v38, v36 row_ror:8 row_mask:0xf bank_mask:0xf
	s_waitcnt lgkmcnt(0)
	v_pk_add_f32 v[36:37], v[36:37], v[38:39]
	s_nop 1
	v_mov_b32_dpp v39, v37 row_ror:4 row_mask:0xf bank_mask:0xf
	s_nop 1
	v_mov_b32_dpp v38, v36 row_ror:4 row_mask:0xf bank_mask:0xf
	s_waitcnt lgkmcnt(0)
	v_pk_add_f32 v[36:37], v[36:37], v[38:39]
	s_nop 1
	v_mov_b32_dpp v39, v37 quad_perm:[2,3,0,1] row_mask:0xf bank_mask:0xf
	s_nop 1
	v_mov_b32_dpp v38, v36 quad_perm:[2,3,0,1] row_mask:0xf bank_mask:0xf
	s_waitcnt lgkmcnt(0)
	v_pk_add_f32 v[36:37], v[36:37], v[38:39]
	s_nop 1
	v_mov_b32_dpp v39, v37 quad_perm:[1,0,3,2] row_mask:0xf bank_mask:0xf
	s_nop 1
	v_mov_b32_dpp v38, v36 quad_perm:[1,0,3,2] row_mask:0xf bank_mask:0xf
	s_waitcnt lgkmcnt(0)
	v_pk_add_f32 v[36:37], v[36:37], v[38:39]
	s_nop 0
	v_pk_fma_f32 v[36:37], v[36:37], s[30:31], v[24:25] op_sel_hi:[1,0,0]
	s_nop 0
	v_mul_f32_e32 v38, 0x4b800000, v37
	v_cmp_gt_f32_e64 s[36:37], s66, v37
	v_cmp_gt_f32_e32 vcc, s66, v36
	s_nop 0
	v_cndmask_b32_e64 v37, v37, v38, s[36:37]
	v_rsq_f32_e32 v37, v37
	s_nop 0
	v_mul_f32_e32 v38, 0x45800000, v37
	v_cndmask_b32_e64 v38, v37, v38, s[36:37]
	v_pk_mul_f32 v[32:33], v[32:33], v[38:39] op_sel_hi:[1,0]
	v_pk_mul_f32 v[34:35], v[34:35], v[38:39] op_sel_hi:[1,0]
	v_pk_mul_f32 v[2:3], v[2:3], v[32:33]
	v_pk_mul_f32 v[0:1], v[0:1], v[34:35]
	v_pk_mul_f32 v[2:3], v[2:3], v[42:43]
	v_pk_mul_f32 v[0:1], v[0:1], v[40:41]
	v_lshlrev_b32_e32 v34, 16, v26
	v_cvt_pk_bf16_f32 v0, v0, v1
	v_cvt_pk_bf16_f32 v1, v2, v3
	global_store_dwordx2 v[16:17], v[0:1], off offset:2048
	v_mul_f32_e32 v0, 0x4b800000, v36
	v_cndmask_b32_e32 v0, v36, v0, vcc
	v_rsq_f32_e32 v0, v0
	v_and_b32_e32 v35, 0xffff0000, v26
	v_lshlrev_b32_e32 v26, 16, v27
	v_and_b32_e32 v27, 0xffff0000, v27
	v_mul_f32_e32 v1, 0x45800000, v0
	v_cndmask_b32_e32 v32, v0, v1, vcc
	v_mov_b64_e32 v[0:1], v[100:101]
	v_mov_b64_e32 v[2:3], v[102:103]
	v_pk_mul_f32 v[30:31], v[30:31], v[32:33] op_sel_hi:[1,0]
	v_pk_mul_f32 v[28:29], v[28:29], v[32:33] op_sel_hi:[1,0]
	v_lshlrev_b32_e32 v32, 16, v20
	v_and_b32_e32 v33, 0xffff0000, v20
	v_lshlrev_b32_e32 v20, 16, v18
	v_pk_mul_f32 v[0:1], v[0:1], v[28:29]
	v_pk_mul_f32 v[2:3], v[2:3], v[30:31]
	v_pk_mul_f32 v[0:1], v[0:1], v[34:35]
	v_pk_mul_f32 v[2:3], v[2:3], v[26:27]
	v_cvt_pk_bf16_f32 v0, v0, v1
	v_cvt_pk_bf16_f32 v1, v2, v3
	v_lshlrev_b32_e32 v26, 16, v22
	v_and_b32_e32 v27, 0xffff0000, v22
	global_store_dwordx2 v[16:17], v[0:1], off offset:2560
	v_lshlrev_b32_e32 v22, 16, v23
	v_add_f32_e32 v0, v26, v27
	v_and_b32_e32 v23, 0xffff0000, v23
	v_add_f32_e32 v0, v0, v22
	v_add_f32_e32 v0, v0, v23
	v_mov_b32_e32 v1, v0
	s_nop 1
	v_permlane32_swap_b32_e32 v1, v0
	v_lshlrev_b32_e32 v34, 16, v21
	v_and_b32_e32 v35, 0xffff0000, v21
	v_and_b32_e32 v21, 0xffff0000, v18
	v_lshlrev_b32_e32 v18, 16, v19
	s_waitcnt lgkmcnt(0)
; __device__ __forceinline__ u32x2 pack4(f32x4 v) { u32x2 r; r[0] = cvt_pk(v[0], v[1]); r[1] = cvt_pk(v[2], v[3]); return r; }
; __device__ __forceinline__ f32x4 unpack4(u32x2 u) { f32x4 r; r[0] = bflo(u[0]); r[1] = bfhi(u[0]); r[2] = bflo(u[1]); r[3] = bfhi(u[1]); return r; }
; __device__ __forceinline__ float wave_sum(float v) {
; #pragma unroll
;   for (int o = 32; o >= 1; o >>= 1) v += __shfl_xor(v, o);
;   return v;
; }
; __device__ __forceinline__ void phase_retpost(const Params& p) {
;     ...
; #pragma unroll
;     for (int q = 0; q < 8; ++q) {
;       const int pr = pr0 + q, r = pr >> 3, h = pr & 7;
;       const f32x4 x = unpack4(xr[q]);
;       const float mean = wave_sum(x[0] + x[1] + x[2] + x[3]) * (1.0f / 256.0f);
;       const f32x4 d = x - mean;
;       const float var = wave_sum(d[0] * d[0] + d[1] * d[1] + d[2] * d[2] + d[3] * d[3]) * (1.0f / 256.0f);
;       const float rstd = rsqrtf(var + LN_EPS);
;       const f32x4 gn = *(const f32x4*)(p.in[12] + h * 256 + 4 * lane);
;       const f32x4 sg = unpack4(sr[q]);
;       *(u32x2*)(ACAT + (size_t)r * 4096 + 1024 + h * 256 + 4 * lane) = pack4(d * rstd * gn * sg);
;     }
;   }
	v_add_f32_e32 v0, v0, v1
	v_mov_b32_e32 v1, v0
	s_nop 1
	v_permlane16_swap_b32_e32 v1, v0
	v_add_f32_e32 v36, v20, v21
	v_and_b32_e32 v19, 0xffff0000, v19
	v_add_f32_e32 v36, v36, v18
	v_add_f32_e32 v36, v36, v19
	s_waitcnt lgkmcnt(0)
	v_add_f32_e32 v0, v0, v1
	s_nop 1
	v_mov_b32_dpp v1, v0 row_ror:8 row_mask:0xf bank_mask:0xf
	v_mov_b32_e32 v37, v36
	s_nop 1
	v_permlane32_swap_b32_e32 v37, v36
	s_waitcnt lgkmcnt(0)
	v_add_f32_e32 v0, v0, v1
	s_nop 1
	v_mov_b32_dpp v1, v0 row_ror:4 row_mask:0xf bank_mask:0xf
	s_waitcnt lgkmcnt(0)
	v_add_f32_e32 v36, v36, v37
	v_mov_b32_e32 v37, v36
	s_nop 1
	v_permlane16_swap_b32_e32 v37, v36
	s_waitcnt lgkmcnt(0)
	v_add_f32_e32 v0, v0, v1
	s_nop 1
	v_mov_b32_dpp v1, v0 quad_perm:[2,3,0,1] row_mask:0xf bank_mask:0xf
	s_waitcnt lgkmcnt(0)
	v_add_f32_e32 v36, v36, v37
	s_nop 1
	v_mov_b32_dpp v37, v36 row_ror:8 row_mask:0xf bank_mask:0xf
	s_waitcnt lgkmcnt(0)
	v_add_f32_e32 v0, v0, v1
	s_nop 1
	v_mov_b32_dpp v1, v0 quad_perm:[1,0,3,2] row_mask:0xf bank_mask:0xf
	s_waitcnt lgkmcnt(0)
	v_add_f32_e32 v36, v36, v37
	s_nop 1
	v_mov_b32_dpp v37, v36 row_ror:4 row_mask:0xf bank_mask:0xf
	s_waitcnt lgkmcnt(0)
	v_add_f32_e32 v0, v0, v1
	v_fmac_f32_e32 v27, 0xbb800000, v0
	v_fmac_f32_e32 v26, 0xbb800000, v0
	v_fmac_f32_e32 v23, 0xbb800000, v0
	v_fmac_f32_e32 v22, 0xbb800000, v0
	v_mov_b64_e32 v[0:1], v[104:105]
	v_mov_b64_e32 v[2:3], v[106:107]
	s_waitcnt lgkmcnt(0)
	v_add_f32_e32 v36, v36, v37
	s_nop 1
	v_mov_b32_dpp v37, v36 quad_perm:[2,3,0,1] row_mask:0xf bank_mask:0xf
	v_pk_mul_f32 v[30:31], v[26:27], v[26:27]
	v_pk_mul_f32 v[28:29], v[22:23], v[22:23]
	v_mov_b32_e32 v41, v30
	s_waitcnt lgkmcnt(0)
	v_add_f32_e32 v36, v36, v37
	s_nop 1
	v_mov_b32_dpp v37, v36 quad_perm:[1,0,3,2] row_mask:0xf bank_mask:0xf
	s_waitcnt lgkmcnt(0)
	v_add_f32_e32 v36, v36, v37
	v_fmac_f32_e32 v21, 0xbb800000, v36
	v_fmac_f32_e32 v20, 0xbb800000, v36
	v_fmac_f32_e32 v19, 0xbb800000, v36
	v_fmac_f32_e32 v18, 0xbb800000, v36
	v_pk_mul_f32 v[38:39], v[20:21], v[20:21]
	v_pk_mul_f32 v[36:37], v[18:19], v[18:19]
	v_mov_b32_e32 v40, v38
	v_mov_b32_e32 v30, v39
	v_pk_add_f32 v[30:31], v[40:41], v[30:31]
	v_mov_b32_e32 v38, v36
	v_mov_b32_e32 v39, v28
	v_pk_add_f32 v[30:31], v[38:39], v[30:31]
	v_mov_b32_e32 v28, v37
	v_pk_add_f32 v[28:29], v[28:29], v[30:31]
	v_mov_b32_e32 v31, v29
	s_nop 1
	v_permlane32_swap_b32_e32 v31, v29
	v_mov_b32_e32 v30, v28
	s_nop 1
	v_permlane32_swap_b32_e32 v30, v28
	s_waitcnt lgkmcnt(0)
	v_pk_add_f32 v[28:29], v[28:29], v[30:31]
	v_mov_b32_e32 v31, v29
	s_nop 1
	v_permlane16_swap_b32_e32 v31, v29
	v_mov_b32_e32 v30, v28
	s_nop 1
	v_permlane16_swap_b32_e32 v30, v28
	s_waitcnt lgkmcnt(0)
	v_pk_add_f32 v[28:29], v[28:29], v[30:31]
	s_nop 1
	v_mov_b32_dpp v31, v29 row_ror:8 row_mask:0xf bank_mask:0xf
	s_nop 1
	v_mov_b32_dpp v30, v28 row_ror:8 row_mask:0xf bank_mask:0xf
	s_waitcnt lgkmcnt(0)
	v_pk_add_f32 v[28:29], v[28:29], v[30:31]
	s_nop 1
	v_mov_b32_dpp v31, v29 row_ror:4 row_mask:0xf bank_mask:0xf
	s_nop 1
	v_mov_b32_dpp v30, v28 row_ror:4 row_mask:0xf bank_mask:0xf
	s_waitcnt lgkmcnt(0)
	v_pk_add_f32 v[28:29], v[28:29], v[30:31]
	s_nop 1
	v_mov_b32_dpp v31, v29 quad_perm:[2,3,0,1] row_mask:0xf bank_mask:0xf
	s_nop 1
	v_mov_b32_dpp v30, v28 quad_perm:[2,3,0,1] row_mask:0xf bank_mask:0xf
	s_waitcnt lgkmcnt(0)
	v_pk_add_f32 v[28:29], v[28:29], v[30:31]
	s_nop 1
	v_mov_b32_dpp v31, v29 quad_perm:[1,0,3,2] row_mask:0xf bank_mask:0xf
	s_nop 1
	v_mov_b32_dpp v30, v28 quad_perm:[1,0,3,2] row_mask:0xf bank_mask:0xf
	s_waitcnt lgkmcnt(0)
	v_pk_add_f32 v[28:29], v[28:29], v[30:31]
	s_nop 0
	v_pk_fma_f32 v[24:25], v[28:29], s[30:31], v[24:25] op_sel_hi:[1,0,0]
	s_nop 0
	v_mul_f32_e32 v28, 0x4b800000, v25
	v_cmp_gt_f32_e64 s[36:37], s66, v25
	v_cmp_gt_f32_e32 vcc, s66, v24
	s_nop 0
	v_cndmask_b32_e64 v25, v25, v28, s[36:37]
	v_rsq_f32_e32 v25, v25
	s_nop 0
	v_mul_f32_e32 v28, 0x45800000, v25
	v_cndmask_b32_e64 v28, v25, v28, s[36:37]
	v_pk_mul_f32 v[22:23], v[22:23], v[28:29] op_sel_hi:[1,0]
	v_pk_mul_f32 v[26:27], v[26:27], v[28:29] op_sel_hi:[1,0]
	v_pk_mul_f32 v[2:3], v[2:3], v[22:23]
	v_pk_mul_f32 v[0:1], v[0:1], v[26:27]
	v_pk_mul_f32 v[2:3], v[2:3], v[34:35]
	v_pk_mul_f32 v[0:1], v[0:1], v[32:33]
	v_and_b32_e32 v25, 0xffff0000, v14
	v_cvt_pk_bf16_f32 v0, v0, v1
	v_cvt_pk_bf16_f32 v1, v2, v3
	global_store_dwordx2 v[16:17], v[0:1], off offset:3072
	v_mul_f32_e32 v0, 0x4b800000, v24
	v_cndmask_b32_e32 v0, v24, v0, vcc
	v_rsq_f32_e32 v0, v0
	v_lshlrev_b32_e32 v24, 16, v14
	v_lshlrev_b32_e32 v14, 16, v15
	v_and_b32_e32 v15, 0xffff0000, v15
	v_mul_f32_e32 v1, 0x45800000, v0
	v_cndmask_b32_e32 v22, v0, v1, vcc
	v_mov_b64_e32 v[0:1], v[108:109]
	v_mov_b64_e32 v[2:3], v[110:111]
	v_pk_mul_f32 v[18:19], v[18:19], v[22:23] op_sel_hi:[1,0]
	v_pk_mul_f32 v[20:21], v[20:21], v[22:23] op_sel_hi:[1,0]
	v_cmp_lt_i32_e32 vcc, s29, v62
	s_or_b64 s[42:43], vcc, s[42:43]
	v_pk_mul_f32 v[0:1], v[0:1], v[20:21]
	v_pk_mul_f32 v[2:3], v[2:3], v[18:19]
	v_pk_mul_f32 v[0:1], v[0:1], v[24:25]
	v_pk_mul_f32 v[2:3], v[2:3], v[14:15]
	v_cvt_pk_bf16_f32 v0, v0, v1
	v_cvt_pk_bf16_f32 v1, v2, v3
	global_store_dwordx2 v[16:17], v[0:1], off offset:3584
	s_andn2_b64 exec, exec, s[42:43]
	s_cbranch_execnz .LBB0_174
